# plain (not nt) stores for XN (P0) and H2 (P6) on top of v33
# speedup vs baseline: 1.0277x; 1.0277x over previous
.LBB0_67:
	s_add_i32 s0, s3, 0xffff7fff
	s_add_u32 s15, s3, -1
	s_addc_u32 s1, s13, -1
	s_cmp_lt_i32 s6, 0x8000
	s_cselect_b32 s1, s1, 0
	s_cselect_b32 s0, s15, s0
	s_cselect_b32 s15, s53, s55
	s_cselect_b32 s18, s52, s54
	s_lshl_b64 s[0:1], s[0:1], 12
	s_add_u32 s0, s18, s0
	s_addc_u32 s1, s15, s1
	s_add_i32 s15, s3, 0xffff8000
	global_load_dwordx4 v[30:33], v77, s[0:1] nt
	global_load_dwordx4 v[22:25], v77, s[0:1] offset:1024 nt
	global_load_dwordx4 v[18:21], v77, s[0:1] offset:3072 nt
	global_load_dwordx4 v[26:29], v77, s[0:1] offset:2048 nt
	s_cmp_lt_i32 s3, 0x8000
	s_cselect_b32 s1, s13, 0
	s_cselect_b32 s0, s3, s15
	s_cselect_b32 s15, s53, s55
	s_cselect_b32 s18, s52, s54
	s_lshl_b64 s[0:1], s[0:1], 12
	s_add_u32 s0, s18, s0
	s_addc_u32 s1, s15, s1
	global_load_dwordx4 v[46:49], v77, s[0:1] nt
	global_load_dwordx4 v[38:41], v77, s[0:1] offset:1024 nt
	global_load_dwordx4 v[34:37], v77, s[0:1] offset:3072 nt
	global_load_dwordx4 v[42:45], v77, s[0:1] offset:2048 nt
	s_add_u32 s0, s3, 1
	s_addc_u32 s1, s13, 0
	s_add_i32 s15, s3, 0xffff8001
	s_cmp_lt_i32 s0, 0x8000
	s_cselect_b32 s1, s1, 0
	s_cselect_b32 s0, s0, s15
	s_cselect_b32 s15, s53, s55
	s_cselect_b32 s18, s52, s54
	s_lshl_b64 s[0:1], s[0:1], 12
	s_add_u32 s0, s18, s0
	s_addc_u32 s1, s15, s1
	global_load_dwordx4 v[14:17], v77, s[0:1] nt
	global_load_dwordx4 v[6:9], v77, s[0:1] offset:1024 nt
	global_load_dwordx4 v[2:5], v77, s[0:1] offset:3072 nt
	global_load_dwordx4 v[10:13], v77, s[0:1] offset:2048 nt
	s_add_u32 s0, s3, 2
	s_addc_u32 s1, s13, 0
	s_add_i32 s15, s3, 0xffff8002
	s_cmp_lt_i32 s0, 0x8000
	s_cselect_b32 s1, s1, 0
	s_cselect_b32 s0, s0, s15
	s_cselect_b32 s15, s53, s55
	s_cselect_b32 s18, s52, s54
	s_lshl_b64 s[0:1], s[0:1], 12
	s_add_u32 s0, s18, s0
	s_addc_u32 s1, s15, s1
	global_load_dwordx4 v[62:65], v77, s[0:1] nt
	global_load_dwordx4 v[58:61], v77, s[0:1] offset:1024 nt
	global_load_dwordx4 v[54:57], v77, s[0:1] offset:2048 nt
	global_load_dwordx4 v[50:53], v77, s[0:1] offset:3072 nt
	s_add_i32 s6, s6, s8
	s_add_u32 s3, s3, s8
	v_add_co_u32_e32 v70, vcc, s14, v66
	s_addc_u32 s13, s13, s9
	s_nop 0
	v_addc_co_u32_e32 v71, vcc, -1, v67, vcc
	s_cmp_lt_i32 s6, 0x10000
	s_waitcnt vmcnt(15)
	v_pk_mul_f32 v[78:79], v[32:33], v[32:33]
	v_pk_mul_f32 v[80:81], v[30:31], v[30:31]
	s_waitcnt vmcnt(14)
	v_pk_mul_f32 v[82:83], v[24:25], v[24:25]
	v_pk_mul_f32 v[84:85], v[22:23], v[22:23]
	v_pk_mov_b32 v[90:91], v[80:81], v[78:79] op_sel:[1,0]
	v_mov_b32_e32 v81, v79
	v_pk_mov_b32 v[78:79], v[84:85], v[82:83] op_sel:[1,0]
	v_mov_b32_e32 v85, v83
	s_waitcnt vmcnt(13)
	v_mul_f32_e32 v89, v18, v18
	s_waitcnt vmcnt(12)
	v_mul_f32_e32 v86, v27, v27
	v_mul_f32_e32 v88, v29, v29
	v_pk_add_f32 v[80:81], v[90:91], v[80:81]
	v_pk_add_f32 v[78:79], v[78:79], v[84:85]
	v_mul_f32_e32 v92, v19, v19
	v_mul_f32_e32 v93, v20, v20
	v_mul_f32_e32 v94, v21, v21
	v_pk_fma_f32 v[82:83], v[26:27], v[26:27], v[86:87] op_sel_hi:[1,1,0]
	v_pk_fma_f32 v[86:87], v[28:29], v[28:29], v[88:89] op_sel_hi:[1,1,0]
	v_pk_add_f32 v[80:81], v[80:81], v[80:81] op_sel:[0,1] op_sel_hi:[1,0]
	v_pk_add_f32 v[78:79], v[78:79], v[78:79] op_sel:[0,1] op_sel_hi:[1,0]
	v_mov_b32_e32 v83, v93
	v_mov_b32_e32 v87, v94
	v_mov_b32_e32 v81, v89
	v_mov_b32_e32 v79, v92
	v_pk_add_f32 v[82:83], v[82:83], v[86:87]
	v_pk_add_f32 v[78:79], v[80:81], v[78:79]
	s_waitcnt vmcnt(11)
	v_pk_mul_f32 v[80:81], v[48:49], v[48:49]
	v_pk_mul_f32 v[84:85], v[46:47], v[46:47]
	s_waitcnt vmcnt(10)
	v_pk_mul_f32 v[86:87], v[40:41], v[40:41]
	v_pk_mul_f32 v[88:89], v[38:39], v[38:39]
	v_pk_add_f32 v[78:79], v[78:79], v[82:83]
	v_pk_mov_b32 v[82:83], v[84:85], v[80:81] op_sel:[1,0]
	v_mov_b32_e32 v85, v81
	v_pk_mov_b32 v[80:81], v[88:89], v[86:87] op_sel:[1,0]
	v_mov_b32_e32 v89, v87
	s_waitcnt vmcnt(9)
	v_mul_f32_e32 v93, v34, v34
	s_waitcnt vmcnt(8)
	v_mul_f32_e32 v90, v43, v43
	v_mul_f32_e32 v92, v45, v45
	v_pk_add_f32 v[82:83], v[82:83], v[84:85]
	v_pk_add_f32 v[80:81], v[80:81], v[88:89]
	v_mul_f32_e32 v94, v35, v35
	v_mul_f32_e32 v95, v36, v36
	v_mul_f32_e32 v96, v37, v37
	v_pk_fma_f32 v[86:87], v[42:43], v[42:43], v[90:91] op_sel_hi:[1,1,0]
	v_pk_fma_f32 v[90:91], v[44:45], v[44:45], v[92:93] op_sel_hi:[1,1,0]
	v_pk_add_f32 v[82:83], v[82:83], v[82:83] op_sel:[0,1] op_sel_hi:[1,0]
	v_pk_add_f32 v[80:81], v[80:81], v[80:81] op_sel:[0,1] op_sel_hi:[1,0]
	v_mov_b32_e32 v87, v95
	v_mov_b32_e32 v91, v96
	v_mov_b32_e32 v83, v93
	v_mov_b32_e32 v81, v94
	v_pk_add_f32 v[86:87], v[86:87], v[90:91]
	v_pk_add_f32 v[80:81], v[82:83], v[80:81]
	v_mov_b32_e32 v85, v78
	v_pk_add_f32 v[80:81], v[80:81], v[86:87]
	s_waitcnt vmcnt(7)
	v_pk_mul_f32 v[82:83], v[16:17], v[16:17]
	v_mov_b32_e32 v84, v80
	v_mov_b32_e32 v78, v81
	v_pk_mul_f32 v[86:87], v[14:15], v[14:15]
	s_waitcnt vmcnt(6)
	v_pk_mul_f32 v[88:89], v[8:9], v[8:9]
	v_pk_mul_f32 v[90:91], v[6:7], v[6:7]
	v_pk_add_f32 v[78:79], v[84:85], v[78:79]
	v_pk_mov_b32 v[94:95], v[86:87], v[82:83] op_sel:[1,0]
	v_mov_b32_e32 v87, v83
	v_pk_mov_b32 v[82:83], v[90:91], v[88:89] op_sel:[1,0]
	v_mov_b32_e32 v91, v89
	ds_bpermute_b32 v89, v1, v79
	ds_bpermute_b32 v88, v1, v78
	s_waitcnt vmcnt(5)
	v_mul_f32_e32 v93, v2, v2
	s_waitcnt vmcnt(4)
	v_mul_f32_e32 v80, v11, v11
	v_mul_f32_e32 v92, v13, v13
	v_pk_add_f32 v[86:87], v[94:95], v[86:87]
	v_pk_add_f32 v[82:83], v[82:83], v[90:91]
	v_mul_f32_e32 v96, v3, v3
	v_mul_f32_e32 v97, v4, v4
	v_mul_f32_e32 v98, v5, v5
	v_pk_fma_f32 v[80:81], v[10:11], v[10:11], v[80:81] op_sel_hi:[1,1,0]
	v_pk_fma_f32 v[84:85], v[12:13], v[12:13], v[92:93] op_sel_hi:[1,1,0]
	v_pk_add_f32 v[86:87], v[86:87], v[86:87] op_sel:[0,1] op_sel_hi:[1,0]
	v_pk_add_f32 v[82:83], v[82:83], v[82:83] op_sel:[0,1] op_sel_hi:[1,0]
	v_mov_b32_e32 v81, v97
	v_mov_b32_e32 v85, v98
	v_mov_b32_e32 v87, v93
	v_mov_b32_e32 v83, v96
	v_pk_add_f32 v[80:81], v[80:81], v[84:85]
	v_pk_add_f32 v[82:83], v[86:87], v[82:83]
	s_waitcnt vmcnt(3)
	v_pk_mul_f32 v[84:85], v[62:63], v[62:63]
	v_pk_add_f32 v[80:81], v[82:83], v[80:81]
	v_pk_mul_f32 v[82:83], v[64:65], v[64:65]
	s_waitcnt vmcnt(2)
	v_pk_mul_f32 v[86:87], v[60:61], v[60:61]
	v_pk_mul_f32 v[90:91], v[58:59], v[58:59]
	s_waitcnt lgkmcnt(0)
	v_pk_add_f32 v[78:79], v[78:79], v[88:89]
	v_pk_mov_b32 v[94:95], v[84:85], v[82:83] op_sel:[1,0]
	v_mov_b32_e32 v85, v83
	v_pk_mov_b32 v[82:83], v[90:91], v[86:87] op_sel:[1,0]
	v_mov_b32_e32 v91, v87
	ds_bpermute_b32 v97, v72, v79
	ds_bpermute_b32 v96, v72, v78
	s_waitcnt vmcnt(1)
	v_mul_f32_e32 v88, v55, v55
	v_mul_f32_e32 v92, v57, v57
	v_mov_b32_e32 v89, v80
	v_pk_add_f32 v[84:85], v[94:95], v[84:85]
	v_pk_add_f32 v[82:83], v[82:83], v[90:91]
	s_waitcnt vmcnt(0)
	v_mul_f32_e32 v98, v50, v50
	v_mul_f32_e32 v99, v51, v51
	v_mul_f32_e32 v100, v52, v52
	v_mul_f32_e32 v101, v53, v53
	v_pk_fma_f32 v[86:87], v[54:55], v[54:55], v[88:89] op_sel_hi:[1,1,0]
	v_pk_fma_f32 v[92:93], v[56:57], v[56:57], v[92:93] op_sel_hi:[1,1,0]
	v_pk_add_f32 v[84:85], v[84:85], v[84:85] op_sel:[0,1] op_sel_hi:[1,0]
	v_pk_add_f32 v[82:83], v[82:83], v[82:83] op_sel:[0,1] op_sel_hi:[1,0]
	v_mov_b32_e32 v87, v100
	v_mov_b32_e32 v93, v101
	v_mov_b32_e32 v85, v98
	v_mov_b32_e32 v83, v99
	v_pk_add_f32 v[86:87], v[86:87], v[92:93]
	v_pk_add_f32 v[82:83], v[84:85], v[82:83]
	s_waitcnt lgkmcnt(0)
	v_pk_add_f32 v[78:79], v[78:79], v[96:97]
	v_pk_add_f32 v[82:83], v[82:83], v[86:87]
	ds_bpermute_b32 v85, v73, v79
	ds_bpermute_b32 v84, v73, v78
	v_mov_b32_e32 v88, v82
	v_mov_b32_e32 v80, v83
	v_pk_add_f32 v[80:81], v[88:89], v[80:81]
	ds_bpermute_b32 v83, v1, v81
	ds_bpermute_b32 v82, v1, v80
	s_waitcnt lgkmcnt(2)
	v_pk_add_f32 v[78:79], v[78:79], v[84:85]
	ds_bpermute_b32 v85, v74, v79
	ds_bpermute_b32 v84, v74, v78
	s_waitcnt lgkmcnt(2)
	v_pk_add_f32 v[80:81], v[80:81], v[82:83]
	ds_bpermute_b32 v83, v72, v81
	ds_bpermute_b32 v82, v72, v80
	s_waitcnt lgkmcnt(2)
	v_pk_add_f32 v[78:79], v[78:79], v[84:85]
	ds_bpermute_b32 v85, v75, v79
	ds_bpermute_b32 v84, v75, v78
	s_waitcnt lgkmcnt(2)
	v_pk_add_f32 v[80:81], v[80:81], v[82:83]
	ds_bpermute_b32 v83, v73, v81
	ds_bpermute_b32 v82, v73, v80
	s_waitcnt lgkmcnt(2)
	v_pk_add_f32 v[78:79], v[78:79], v[84:85]
	ds_bpermute_b32 v85, v76, v79
	ds_bpermute_b32 v84, v76, v78
	s_waitcnt lgkmcnt(2)
	v_pk_add_f32 v[80:81], v[80:81], v[82:83]
	ds_bpermute_b32 v83, v74, v81
	ds_bpermute_b32 v82, v74, v80
	s_waitcnt lgkmcnt(2)
	v_pk_add_f32 v[78:79], v[78:79], v[84:85]
	s_waitcnt lgkmcnt(0)
	v_pk_add_f32 v[80:81], v[80:81], v[82:83]
	v_pk_fma_f32 v[78:79], v[78:79], s[12:13], v[68:69] op_sel_hi:[1,0,0]
	s_nop 0
	v_mul_f32_e32 v84, 0x4b800000, v79
	v_mul_f32_e32 v85, 0x4b800000, v78
	v_cmp_gt_f32_e32 vcc, s7, v78
	v_cmp_gt_f32_e64 s[0:1], s7, v79
	s_nop 0
	v_cndmask_b32_e32 v83, v78, v85, vcc
	v_cndmask_b32_e64 v82, v79, v84, s[0:1]
	ds_bpermute_b32 v79, v75, v81
	ds_bpermute_b32 v78, v75, v80
	v_rsq_f32_e32 v82, v82
	v_rsq_f32_e32 v83, v83
	v_mul_f32_e32 v84, 0x45800000, v82
	v_mul_f32_e32 v85, 0x45800000, v83
	s_waitcnt lgkmcnt(0)
	v_pk_add_f32 v[78:79], v[80:81], v[78:79]
	v_cndmask_b32_e64 v80, v82, v84, s[0:1]
	v_cndmask_b32_e32 v82, v83, v85, vcc
	ds_bpermute_b32 v85, v76, v79
	ds_bpermute_b32 v84, v76, v78
	v_pk_mul_f32 v[30:31], v[30:31], v[80:81] op_sel_hi:[1,0]
	v_pk_mul_f32 v[32:33], v[32:33], v[80:81] op_sel_hi:[1,0]
	v_pk_mul_f32 v[18:19], v[18:19], v[80:81] op_sel_hi:[1,0]
	v_pk_mul_f32 v[20:21], v[20:21], v[80:81] op_sel_hi:[1,0]
	v_pk_mul_f32 v[22:23], v[22:23], v[80:81] op_sel_hi:[1,0]
	v_pk_mul_f32 v[24:25], v[24:25], v[80:81] op_sel_hi:[1,0]
	v_pk_mul_f32 v[26:27], v[26:27], v[80:81] op_sel_hi:[1,0]
	v_pk_mul_f32 v[28:29], v[28:29], v[80:81] op_sel_hi:[1,0]
	v_pk_mul_f32 v[46:47], v[46:47], v[82:83] op_sel_hi:[1,0]
	v_pk_mul_f32 v[48:49], v[48:49], v[82:83] op_sel_hi:[1,0]
	v_pk_mul_f32 v[38:39], v[38:39], v[82:83] op_sel_hi:[1,0]
	v_pk_mul_f32 v[40:41], v[40:41], v[82:83] op_sel_hi:[1,0]
	v_pk_mul_f32 v[42:43], v[42:43], v[82:83] op_sel_hi:[1,0]
	v_pk_mul_f32 v[44:45], v[44:45], v[82:83] op_sel_hi:[1,0]
	v_pk_mul_f32 v[34:35], v[34:35], v[82:83] op_sel_hi:[1,0]
	v_pk_mul_f32 v[36:37], v[36:37], v[82:83] op_sel_hi:[1,0]
	v_cvt_pk_bf16_f32 v30, v30, v31
	v_cvt_pk_bf16_f32 v31, v32, v33
	v_cvt_pk_bf16_f32 v18, v18, v19
	v_cvt_pk_bf16_f32 v19, v20, v21
	v_cvt_pk_bf16_f32 v22, v22, v23
	v_cvt_pk_bf16_f32 v23, v24, v25
	v_cvt_pk_bf16_f32 v24, v26, v27
	v_cvt_pk_bf16_f32 v25, v28, v29
	v_cvt_pk_bf16_f32 v20, v46, v47
	v_cvt_pk_bf16_f32 v21, v48, v49
	v_cvt_pk_bf16_f32 v26, v38, v39
	v_cvt_pk_bf16_f32 v27, v40, v41
	v_cvt_pk_bf16_f32 v28, v42, v43
	v_cvt_pk_bf16_f32 v29, v44, v45
	v_cvt_pk_bf16_f32 v32, v34, v35
	v_cvt_pk_bf16_f32 v33, v36, v37
	global_store_dwordx2 v[70:71], v[30:31], off offset:-3584
	global_store_dwordx2 v[70:71], v[22:23], off offset:-3072
	global_store_dwordx2 v[70:71], v[24:25], off offset:-2560
	global_store_dwordx2 v[70:71], v[18:19], off offset:-2048
	global_store_dwordx2 v[70:71], v[20:21], off offset:-1536
	global_store_dwordx2 v[70:71], v[26:27], off offset:-1024
	global_store_dwordx2 v[70:71], v[28:29], off offset:-512
	global_store_dwordx2 v[66:67], v[32:33], off offset:-4096
	s_waitcnt lgkmcnt(0)
	v_pk_add_f32 v[18:19], v[78:79], v[84:85]
	s_nop 0
	v_pk_fma_f32 v[18:19], v[18:19], s[12:13], v[68:69] op_sel_hi:[1,0,0]
	s_nop 0
	v_mul_f32_e32 v20, 0x4b800000, v19
	v_cmp_gt_f32_e64 s[0:1], s7, v19
	v_mul_f32_e32 v21, 0x4b800000, v18
	v_cmp_gt_f32_e32 vcc, s7, v18
	v_cndmask_b32_e64 v19, v19, v20, s[0:1]
	v_rsq_f32_e32 v19, v19
	v_cndmask_b32_e32 v18, v18, v21, vcc
	v_rsq_f32_e32 v20, v18
	v_mul_f32_e32 v18, 0x45800000, v19
	v_cndmask_b32_e64 v18, v19, v18, s[0:1]
	v_mul_f32_e32 v21, 0x45800000, v20
	v_cndmask_b32_e32 v20, v20, v21, vcc
	v_pk_mul_f32 v[14:15], v[14:15], v[18:19] op_sel_hi:[1,0]
	v_pk_mul_f32 v[16:17], v[16:17], v[18:19] op_sel_hi:[1,0]
	v_pk_mul_f32 v[6:7], v[6:7], v[18:19] op_sel_hi:[1,0]
	v_pk_mul_f32 v[8:9], v[8:9], v[18:19] op_sel_hi:[1,0]
	v_pk_mul_f32 v[10:11], v[10:11], v[18:19] op_sel_hi:[1,0]
	v_pk_mul_f32 v[12:13], v[12:13], v[18:19] op_sel_hi:[1,0]
	v_pk_mul_f32 v[2:3], v[2:3], v[18:19] op_sel_hi:[1,0]
	v_pk_mul_f32 v[4:5], v[4:5], v[18:19] op_sel_hi:[1,0]
	v_pk_mul_f32 v[18:19], v[62:63], v[20:21] op_sel_hi:[1,0]
	v_pk_mul_f32 v[22:23], v[64:65], v[20:21] op_sel_hi:[1,0]
	v_pk_mul_f32 v[24:25], v[58:59], v[20:21] op_sel_hi:[1,0]
	v_pk_mul_f32 v[26:27], v[60:61], v[20:21] op_sel_hi:[1,0]
	v_pk_mul_f32 v[28:29], v[54:55], v[20:21] op_sel_hi:[1,0]
	v_pk_mul_f32 v[30:31], v[56:57], v[20:21] op_sel_hi:[1,0]
	v_pk_mul_f32 v[32:33], v[50:51], v[20:21] op_sel_hi:[1,0]
	v_pk_mul_f32 v[20:21], v[52:53], v[20:21] op_sel_hi:[1,0]
	v_cvt_pk_bf16_f32 v14, v14, v15
	v_cvt_pk_bf16_f32 v15, v16, v17
	v_cvt_pk_bf16_f32 v6, v6, v7
	v_cvt_pk_bf16_f32 v7, v8, v9
	v_cvt_pk_bf16_f32 v8, v10, v11
	v_cvt_pk_bf16_f32 v9, v12, v13
	v_cvt_pk_bf16_f32 v2, v2, v3
	v_cvt_pk_bf16_f32 v3, v4, v5
	v_cvt_pk_bf16_f32 v4, v18, v19
	v_cvt_pk_bf16_f32 v5, v22, v23
	v_cvt_pk_bf16_f32 v10, v24, v25
	v_cvt_pk_bf16_f32 v11, v26, v27
	v_cvt_pk_bf16_f32 v12, v28, v29
	v_cvt_pk_bf16_f32 v13, v30, v31
	v_cvt_pk_bf16_f32 v16, v32, v33
	v_cvt_pk_bf16_f32 v17, v20, v21
	global_store_dwordx2 v[66:67], v[14:15], off offset:-3584
	global_store_dwordx2 v[66:67], v[6:7], off offset:-3072
	global_store_dwordx2 v[66:67], v[8:9], off offset:-2560
	global_store_dwordx2 v[66:67], v[2:3], off offset:-2048
	global_store_dwordx2 v[66:67], v[4:5], off offset:-1536
	global_store_dwordx2 v[66:67], v[10:11], off offset:-1024
	global_store_dwordx2 v[66:67], v[12:13], off offset:-512
	global_store_dwordx2 v[66:67], v[16:17], off
	v_lshl_add_u64 v[66:67], v[66:67], 0, s[10:11]
	s_cbranch_scc1 .LBB0_67

.LBB0_795:
	v_add_co_u32_e32 v56, vcc, s7, v48
	s_add_u32 s4, s0, -1
	s_nop 0
	v_addc_co_u32_e32 v57, vcc, -1, v49, vcc
	v_add_co_u32_e32 v58, vcc, s21, v48
	s_addc_u32 s5, s1, -1
	s_nop 0
	v_addc_co_u32_e32 v59, vcc, -1, v49, vcc
	s_add_u32 s24, s82, s16
	v_add_co_u32_e32 v60, vcc, s22, v48
	s_addc_u32 s25, s83, s17
	v_lshl_add_u64 v[54:55], s[82:83], 0, v[50:51]
	v_addc_co_u32_e32 v61, vcc, -1, v49, vcc
	s_add_u32 s26, s24, 0x9100000
	v_add_co_u32_e32 v62, vcc, s3, v54
	s_addc_u32 s27, s25, 0
	s_add_i32 s23, s0, 0xffff7fff
	v_addc_co_u32_e32 v63, vcc, 0, v55, vcc
	s_cmp_lt_i32 s6, 0x8000
	global_load_dwordx2 v[142:143], v[54:55], off nt
	global_load_dwordx2 v[176:177], v[54:55], off offset:512 nt
	global_load_dwordx2 v[178:179], v[54:55], off offset:1024 nt
	global_load_dwordx2 v[180:181], v[54:55], off offset:1536 nt
	global_load_dwordx2 v[182:183], v[54:55], off offset:2048 nt
	global_load_dwordx2 v[184:185], v[54:55], off offset:2560 nt
	global_load_dwordx2 v[186:187], v[54:55], off offset:3072 nt
	global_load_dwordx2 v[188:189], v[54:55], off offset:3584 nt
	global_load_dwordx2 v[190:191], v[62:63], off nt
	global_load_dwordx2 v[192:193], v[62:63], off offset:512 nt
	global_load_dwordx2 v[194:195], v[62:63], off offset:1024 nt
	global_load_dwordx2 v[196:197], v[62:63], off offset:1536 nt
	global_load_dwordx2 v[198:199], v[62:63], off offset:2048 nt
	global_load_dwordx2 v[200:201], v[62:63], off offset:2560 nt
	global_load_dwordx2 v[202:203], v[62:63], off offset:3072 nt
	global_load_dwordx2 v[204:205], v[62:63], off offset:3584 nt
	global_load_dwordx4 v[72:75], v70, s[24:25]
	global_load_dwordx4 v[76:79], v70, s[24:25] offset:64
	global_load_dwordx4 v[80:83], v70, s[24:25] offset:128
	global_load_dwordx4 v[84:87], v70, s[24:25] offset:192
	s_cselect_b32 s5, s5, 0
	s_cselect_b32 s4, s4, s23
	global_load_dwordx4 v[88:91], v129, s[26:27] offset:48
	global_load_dwordx4 v[92:95], v129, s[26:27] offset:32
	global_load_dwordx4 v[96:99], v129, s[26:27] offset:16
	s_cselect_b32 s23, s53, s55
	s_cselect_b32 s26, s52, s54
	s_lshl_b64 s[4:5], s[4:5], 12
	s_add_u32 s4, s26, s4
	s_addc_u32 s5, s23, s5
	global_load_dwordx4 v[100:103], v128, s[4:5] nt
	global_load_dwordx4 v[104:107], v128, s[4:5] offset:1024 nt
	global_load_dwordx4 v[108:111], v128, s[4:5] offset:2048 nt
	global_load_dwordx4 v[112:115], v128, s[4:5] offset:3072 nt
	s_add_u32 s4, s24, 0x9100040
	s_addc_u32 s5, s25, 0
	s_add_i32 s23, s0, 0xffff8000
	global_load_dwordx4 v[116:119], v129, s[4:5] offset:48
	global_load_dwordx4 v[120:123], v129, s[4:5] offset:32
	global_load_dwordx4 v[124:127], v129, s[4:5] offset:16
	s_cmp_lt_i32 s0, 0x8000
	s_cselect_b32 s5, s1, 0
	s_cselect_b32 s4, s0, s23
	s_cselect_b32 s23, s53, s55
	s_cselect_b32 s26, s52, s54
	s_lshl_b64 s[4:5], s[4:5], 12
	s_add_u32 s4, s26, s4
	s_addc_u32 s5, s23, s5
	s_add_u32 s23, s0, 1
	s_addc_u32 s26, s1, 0
	global_load_dwordx4 v[130:133], v128, s[4:5] nt
	global_load_dwordx4 v[134:137], v128, s[4:5] offset:1024 nt
	global_load_dwordx4 v[138:141], v128, s[4:5] offset:2048 nt
	global_load_dwordx4 v[146:149], v128, s[4:5] offset:3072 nt
	s_add_u32 s4, s24, 0x9100080
	s_addc_u32 s5, s25, 0
	s_add_i32 s27, s0, 0xffff8001
	s_cmp_lt_i32 s23, 0x8000
	global_load_dwordx4 v[150:153], v129, s[4:5] offset:48
	global_load_dwordx4 v[154:157], v129, s[4:5] offset:32
	global_load_dwordx4 v[158:161], v129, s[4:5] offset:16
	s_cselect_b32 s5, s26, 0
	s_cselect_b32 s4, s23, s27
	s_cselect_b32 s23, s53, s55
	s_cselect_b32 s26, s52, s54
	s_lshl_b64 s[4:5], s[4:5], 12
	s_add_u32 s4, s26, s4
	s_addc_u32 s5, s23, s5
	s_add_u32 s23, s0, 2
	s_addc_u32 s26, s1, 0
	global_load_dwordx4 v[28:31], v128, s[4:5] nt
	global_load_dwordx4 v[24:27], v128, s[4:5] offset:1024 nt
	global_load_dwordx4 v[20:23], v128, s[4:5] offset:2048 nt
	global_load_dwordx4 v[16:19], v128, s[4:5] offset:3072 nt
	s_add_u32 s4, s24, 0x91000c0
	s_addc_u32 s5, s25, 0
	global_load_dwordx4 v[164:167], v129, s[4:5] offset:48
	global_load_dwordx4 v[168:171], v129, s[4:5] offset:32
	global_load_dwordx4 v[172:175], v129, s[4:5] offset:16
	s_add_i32 s24, s0, 0xffff8002
	s_cmp_lt_i32 s23, 0x8000
	s_cselect_b32 s5, s26, 0
	s_cselect_b32 s4, s23, s24
	s_cselect_b32 s23, s53, s55
	s_cselect_b32 s24, s52, s54
	s_lshl_b64 s[4:5], s[4:5], 12
	s_add_u32 s4, s24, s4
	s_addc_u32 s5, s23, s5
	global_load_dwordx4 v[44:47], v128, s[4:5] nt
	global_load_dwordx4 v[40:43], v128, s[4:5] offset:1024 nt
	global_load_dwordx4 v[36:39], v128, s[4:5] offset:2048 nt
	global_load_dwordx4 v[32:35], v128, s[4:5] offset:3072 nt
	s_add_i32 s6, s6, s10
	s_add_u32 s0, s0, s10
	s_addc_u32 s1, s1, s11
	s_add_u32 s16, s16, s18
	s_addc_u32 s17, s17, s19
	v_lshl_add_u64 v[50:51], v[50:51], 0, s[14:15]
	s_cmp_lt_i32 s6, 0x10000
	s_waitcnt vmcnt(47)
	v_lshlrev_b32_e32 v206, 16, v142
	v_and_b32_e32 v207, 0xffff0000, v142
	v_lshlrev_b32_e32 v142, 16, v143
	v_and_b32_e32 v143, 0xffff0000, v143
	s_waitcnt vmcnt(46)
	v_lshlrev_b32_e32 v208, 16, v176
	v_and_b32_e32 v209, 0xffff0000, v176
	s_waitcnt vmcnt(31)
	v_mov_b32_e32 v238, v73
	v_mov_b32_e32 v239, v74
	v_mov_b32_e32 v73, v75
	s_waitcnt vmcnt(30)
	v_mov_b32_e32 v74, v77
	v_mov_b32_e32 v75, v78
	v_mov_b32_e32 v77, v79
	s_waitcnt vmcnt(29)
	v_mov_b32_e32 v78, v81
	v_mov_b32_e32 v79, v82
	v_mov_b32_e32 v81, v83
	s_waitcnt vmcnt(28)
	v_mov_b32_e32 v82, v85
	v_mov_b32_e32 v83, v86
	v_mov_b32_e32 v85, v87
	v_pk_add_f32 v[74:75], v[74:75], v[76:77]
	v_pk_add_f32 v[76:77], v[78:79], v[80:81]
	v_pk_add_f32 v[78:79], v[82:83], v[84:85]
	s_waitcnt vmcnt(25)
	v_mov_b32_e32 v80, v97
	v_mov_b32_e32 v81, v98
	v_mov_b32_e32 v97, v99
	v_pk_add_f32 v[72:73], v[238:239], v[72:73]
	v_pk_add_f32 v[238:239], v[78:79], v[78:79] op_sel:[0,1] op_sel_hi:[1,0]
	v_pk_add_f32 v[78:79], v[80:81], v[96:97]
	v_pk_add_f32 v[72:73], v[72:73], v[72:73] op_sel:[0,1] op_sel_hi:[1,0]
	v_pk_add_f32 v[78:79], v[78:79], v[78:79] op_sel:[0,1] op_sel_hi:[1,0]
	v_add_f32_e32 v82, v92, v93
	v_add_f32_e32 v84, v94, v95
	v_mov_b32_e32 v83, v90
	v_mov_b32_e32 v85, v91
	v_mov_b32_e32 v73, v88
	v_mov_b32_e32 v79, v89
	v_pk_add_f32 v[80:81], v[82:83], v[84:85]
	v_pk_add_f32 v[72:73], v[72:73], v[78:79]
	v_pk_add_f32 v[74:75], v[74:75], v[74:75] op_sel:[0,1] op_sel_hi:[1,0]
	v_pk_add_f32 v[72:73], v[72:73], v[80:81]
	s_waitcnt vmcnt(18)
	v_mov_b32_e32 v80, v125
	v_mov_b32_e32 v81, v126
	v_mov_b32_e32 v125, v127
	v_pk_add_f32 v[80:81], v[80:81], v[124:125]
	v_add_f32_e32 v82, v120, v121
	v_pk_add_f32 v[80:81], v[80:81], v[80:81] op_sel:[0,1] op_sel_hi:[1,0]
	v_add_f32_e32 v84, v122, v123
	v_mov_b32_e32 v75, v116
	v_mov_b32_e32 v83, v118
	v_mov_b32_e32 v85, v119
	v_mov_b32_e32 v81, v117
	v_pk_add_f32 v[82:83], v[82:83], v[84:85]
	v_pk_add_f32 v[74:75], v[74:75], v[80:81]
	v_mov_b32_e32 v79, v72
	v_pk_add_f32 v[74:75], v[74:75], v[82:83]
	s_waitcnt vmcnt(12)
	v_add_f32_e32 v80, v156, v157
	v_mov_b32_e32 v78, v74
	v_mov_b32_e32 v72, v75
	v_pk_add_f32 v[72:73], v[78:79], v[72:73]
	s_waitcnt vmcnt(11)
	v_mov_b32_e32 v74, v159
	v_pk_fma_f32 v[72:73], v[72:73], s[20:21], v[52:53] op_sel_hi:[1,0,0]
	v_mov_b32_e32 v75, v160
	v_mul_f32_e32 v71, 0x4b800000, v73
	v_mul_f32_e32 v82, 0x4b800000, v72
	v_cmp_gt_f32_e32 vcc, s2, v72
	v_cmp_gt_f32_e64 s[4:5], s2, v73
	v_mov_b32_e32 v159, v161
	v_add_f32_e32 v78, v154, v155
	v_mov_b32_e32 v79, v152
	v_mov_b32_e32 v81, v153
	v_cndmask_b32_e64 v71, v73, v71, s[4:5]
	v_cndmask_b32_e32 v82, v72, v82, vcc
	v_pk_add_f32 v[72:73], v[74:75], v[158:159]
	v_pk_add_f32 v[74:75], v[78:79], v[80:81]
	v_rsq_f32_e32 v71, v71
	v_rsq_f32_e32 v78, v82
	v_pk_add_f32 v[76:77], v[76:77], v[76:77] op_sel:[0,1] op_sel_hi:[1,0]
	v_pk_add_f32 v[72:73], v[72:73], v[72:73] op_sel:[0,1] op_sel_hi:[1,0]
	v_mov_b32_e32 v77, v150
	v_mov_b32_e32 v73, v151
	v_pk_add_f32 v[72:73], v[76:77], v[72:73]
	v_lshlrev_b32_e32 v176, 16, v177
	v_pk_add_f32 v[116:117], v[72:73], v[74:75]
	v_mul_f32_e32 v72, 0x45800000, v71
	v_mul_f32_e32 v73, 0x45800000, v78
	v_and_b32_e32 v177, 0xffff0000, v177
	v_lshlrev_b32_e32 v210, 16, v178
	v_and_b32_e32 v211, 0xffff0000, v178
	v_lshlrev_b32_e32 v178, 16, v179
	v_and_b32_e32 v179, 0xffff0000, v179
	v_lshlrev_b32_e32 v212, 16, v180
	v_and_b32_e32 v213, 0xffff0000, v180
	v_lshlrev_b32_e32 v180, 16, v181
	v_and_b32_e32 v181, 0xffff0000, v181
	v_lshlrev_b32_e32 v214, 16, v182
	v_and_b32_e32 v215, 0xffff0000, v182
	v_lshlrev_b32_e32 v182, 16, v183
	v_and_b32_e32 v183, 0xffff0000, v183
	v_lshlrev_b32_e32 v216, 16, v184
	v_and_b32_e32 v217, 0xffff0000, v184
	v_lshlrev_b32_e32 v184, 16, v185
	v_and_b32_e32 v185, 0xffff0000, v185
	v_cndmask_b32_e64 v72, v71, v72, s[4:5]
	v_cndmask_b32_e32 v74, v78, v73, vcc
	v_lshlrev_b32_e32 v218, 16, v186
	v_and_b32_e32 v219, 0xffff0000, v186
	v_lshlrev_b32_e32 v186, 16, v187
	v_and_b32_e32 v187, 0xffff0000, v187
	v_lshlrev_b32_e32 v220, 16, v188
	v_and_b32_e32 v221, 0xffff0000, v188
	v_lshlrev_b32_e32 v188, 16, v189
	v_and_b32_e32 v189, 0xffff0000, v189
	v_pk_mul_f32 v[76:77], v[72:73], v[206:207] op_sel_hi:[0,1]
	v_pk_mul_f32 v[78:79], v[72:73], v[142:143] op_sel_hi:[0,1]
	v_pk_mul_f32 v[80:81], v[72:73], v[208:209] op_sel_hi:[0,1]
	v_pk_mul_f32 v[82:83], v[72:73], v[176:177] op_sel_hi:[0,1]
	v_pk_mul_f32 v[84:85], v[72:73], v[210:211] op_sel_hi:[0,1]
	v_pk_mul_f32 v[86:87], v[72:73], v[178:179] op_sel_hi:[0,1]
	v_pk_mul_f32 v[88:89], v[72:73], v[212:213] op_sel_hi:[0,1]
	v_pk_mul_f32 v[90:91], v[72:73], v[180:181] op_sel_hi:[0,1]
	v_pk_mul_f32 v[92:93], v[74:75], v[214:215] op_sel_hi:[0,1]
	v_pk_mul_f32 v[94:95], v[74:75], v[182:183] op_sel_hi:[0,1]
	v_pk_mul_f32 v[96:97], v[74:75], v[216:217] op_sel_hi:[0,1]
	v_pk_mul_f32 v[98:99], v[74:75], v[184:185] op_sel_hi:[0,1]
	v_pk_mul_f32 v[120:121], v[74:75], v[218:219] op_sel_hi:[0,1]
	v_pk_mul_f32 v[122:123], v[74:75], v[186:187] op_sel_hi:[0,1]
	v_pk_mul_f32 v[124:125], v[74:75], v[220:221] op_sel_hi:[0,1]
	v_pk_mul_f32 v[126:127], v[74:75], v[188:189] op_sel_hi:[0,1]
	s_waitcnt vmcnt(4)
	v_mov_b32_e32 v142, v173
	v_mov_b32_e32 v143, v174
	v_mov_b32_e32 v173, v175
	v_pk_fma_f32 v[74:75], v[2:3], v[78:79], v[102:103]
	v_pk_fma_f32 v[72:73], v[0:1], v[76:77], v[100:101]
	v_pk_fma_f32 v[78:79], v[6:7], v[82:83], v[106:107]
	v_pk_fma_f32 v[76:77], v[4:5], v[80:81], v[104:105]
	v_pk_fma_f32 v[82:83], v[10:11], v[86:87], v[110:111]
	v_pk_fma_f32 v[80:81], v[8:9], v[84:85], v[108:109]
	v_pk_fma_f32 v[86:87], v[14:15], v[90:91], v[114:115]
	v_pk_fma_f32 v[84:85], v[12:13], v[88:89], v[112:113]
	v_pk_fma_f32 v[90:91], v[2:3], v[94:95], v[132:133]
	v_pk_fma_f32 v[88:89], v[0:1], v[92:93], v[130:131]
	v_pk_fma_f32 v[94:95], v[6:7], v[98:99], v[136:137]
	v_pk_fma_f32 v[92:93], v[4:5], v[96:97], v[134:135]
	v_pk_fma_f32 v[98:99], v[10:11], v[122:123], v[140:141]
	v_pk_fma_f32 v[96:97], v[8:9], v[120:121], v[138:139]
	v_pk_fma_f32 v[102:103], v[14:15], v[126:127], v[148:149]
	v_pk_fma_f32 v[100:101], v[12:13], v[124:125], v[146:147]
	v_pk_add_f32 v[104:105], v[142:143], v[172:173]
	v_pk_mul_f32 v[108:109], v[74:75], v[74:75]
	v_pk_mul_f32 v[110:111], v[72:73], v[72:73]
	v_pk_mul_f32 v[112:113], v[78:79], v[78:79]
	v_pk_mul_f32 v[114:115], v[76:77], v[76:77]
	v_pk_mul_f32 v[120:121], v[90:91], v[90:91]
	v_pk_mul_f32 v[122:123], v[88:89], v[88:89]
	v_pk_mul_f32 v[124:125], v[94:95], v[94:95]
	v_pk_mul_f32 v[126:127], v[92:93], v[92:93]
	global_store_dwordx4 v[56:57], v[72:75], off offset:-3072 nt
	global_store_dwordx4 v[56:57], v[76:79], off offset:-2048 nt
	global_store_dwordx4 v[56:57], v[80:83], off offset:-1024 nt
	global_store_dwordx4 v[58:59], v[84:87], off offset:-4096 nt
	global_store_dwordx4 v[58:59], v[88:91], off offset:-3072 nt
	global_store_dwordx4 v[58:59], v[92:95], off offset:-2048 nt
	global_store_dwordx4 v[58:59], v[96:99], off offset:-1024 nt
	global_store_dwordx4 v[58:59], v[100:103], off nt
	v_pk_add_f32 v[58:59], v[104:105], v[104:105] op_sel:[0,1] op_sel_hi:[1,0]
	v_pk_mov_b32 v[104:105], v[110:111], v[108:109] op_sel:[1,0]
	v_mov_b32_e32 v111, v109
	v_pk_mov_b32 v[108:109], v[114:115], v[112:113] op_sel:[1,0]
	v_mov_b32_e32 v115, v113
	v_pk_mov_b32 v[132:133], v[122:123], v[120:121] op_sel:[1,0]
	v_mov_b32_e32 v123, v121
	v_pk_mov_b32 v[120:121], v[126:127], v[124:125] op_sel:[1,0]
	v_mov_b32_e32 v127, v125
	v_mov_b32_e32 v119, v116
	v_add_f32_e32 v150, v168, v169
	v_add_f32_e32 v152, v170, v171
	v_mov_b32_e32 v239, v164
	v_mov_b32_e32 v151, v166
	v_mov_b32_e32 v153, v167
	v_mul_f32_e32 v56, v81, v81
	v_mul_f32_e32 v116, v83, v83
	v_mul_f32_e32 v118, v97, v97
	v_mul_f32_e32 v130, v99, v99
	v_mov_b32_e32 v59, v165
	v_pk_add_f32 v[104:105], v[104:105], v[110:111]
	v_pk_add_f32 v[108:109], v[108:109], v[114:115]
	v_pk_add_f32 v[110:111], v[132:133], v[122:123]
	v_pk_add_f32 v[114:115], v[120:121], v[126:127]
	v_pk_add_f32 v[106:107], v[150:151], v[152:153]
	v_mul_f32_e32 v71, v84, v84
	v_mul_f32_e32 v134, v85, v85
	v_mul_f32_e32 v135, v86, v86
	v_mul_f32_e32 v136, v87, v87
	v_mul_f32_e32 v137, v100, v100
	v_mul_f32_e32 v138, v101, v101
	v_mul_f32_e32 v139, v102, v102
	v_mul_f32_e32 v140, v103, v103
	v_pk_fma_f32 v[56:57], v[80:81], v[80:81], v[56:57] op_sel_hi:[1,1,0]
	v_pk_fma_f32 v[112:113], v[82:83], v[82:83], v[116:117] op_sel_hi:[1,1,0]
	v_pk_fma_f32 v[124:125], v[96:97], v[96:97], v[118:119] op_sel_hi:[1,1,0]
	v_pk_fma_f32 v[130:131], v[98:99], v[98:99], v[130:131] op_sel_hi:[1,1,0]
	v_pk_add_f32 v[58:59], v[238:239], v[58:59]
	v_pk_add_f32 v[104:105], v[104:105], v[104:105] op_sel:[0,1] op_sel_hi:[1,0]
	v_pk_add_f32 v[108:109], v[108:109], v[108:109] op_sel:[0,1] op_sel_hi:[1,0]
	v_pk_add_f32 v[110:111], v[110:111], v[110:111] op_sel:[0,1] op_sel_hi:[1,0]
	v_pk_add_f32 v[114:115], v[114:115], v[114:115] op_sel:[0,1] op_sel_hi:[1,0]
	v_mov_b32_e32 v57, v71
	v_mov_b32_e32 v113, v134
	v_mov_b32_e32 v125, v137
	v_mov_b32_e32 v131, v138
	v_pk_add_f32 v[58:59], v[58:59], v[106:107]
	v_mov_b32_e32 v105, v135
	v_mov_b32_e32 v109, v136
	v_mov_b32_e32 v111, v139
	v_mov_b32_e32 v115, v140
	v_pk_add_f32 v[56:57], v[56:57], v[112:113]
	v_pk_add_f32 v[112:113], v[124:125], v[130:131]
	v_mov_b32_e32 v118, v58
	v_mov_b32_e32 v116, v59
	v_pk_add_f32 v[58:59], v[104:105], v[108:109]
	v_pk_add_f32 v[104:105], v[110:111], v[114:115]
	v_pk_add_f32 v[106:107], v[118:119], v[116:117]
	v_pk_add_f32 v[56:57], v[56:57], v[58:59]
	v_pk_add_f32 v[58:59], v[112:113], v[104:105]
	v_pk_fma_f32 v[104:105], v[106:107], s[20:21], v[52:53] op_sel_hi:[1,0,0]
	v_mov_b32_e32 v106, v58
	v_mov_b32_e32 v107, v56
	v_mov_b32_e32 v56, v59
	v_mul_f32_e32 v58, 0x4b800000, v105
	v_mul_f32_e32 v59, 0x4b800000, v104
	v_cmp_gt_f32_e32 vcc, s2, v104
	v_pk_add_f32 v[56:57], v[106:107], v[56:57]
	v_cmp_gt_f32_e64 s[4:5], s2, v105
	v_cndmask_b32_e32 v104, v104, v59, vcc
	ds_bpermute_b32 v59, v64, v57
	v_cndmask_b32_e64 v71, v105, v58, s[4:5]
	ds_bpermute_b32 v58, v64, v56
	v_rsq_f32_e32 v71, v71
	v_rsq_f32_e32 v104, v104
	v_lshlrev_b32_e32 v222, 16, v190
	v_and_b32_e32 v223, 0xffff0000, v190
	v_mul_f32_e32 v105, 0x45800000, v71
	v_mul_f32_e32 v106, 0x45800000, v104
	s_waitcnt lgkmcnt(0)
	v_pk_add_f32 v[56:57], v[56:57], v[58:59]
	v_lshlrev_b32_e32 v190, 16, v191
	v_and_b32_e32 v191, 0xffff0000, v191
	v_lshlrev_b32_e32 v224, 16, v192
	v_and_b32_e32 v225, 0xffff0000, v192
	v_lshlrev_b32_e32 v192, 16, v193
	v_and_b32_e32 v193, 0xffff0000, v193
	v_lshlrev_b32_e32 v226, 16, v194
	v_and_b32_e32 v227, 0xffff0000, v194
	v_lshlrev_b32_e32 v194, 16, v195
	v_and_b32_e32 v195, 0xffff0000, v195
	v_lshlrev_b32_e32 v230, 16, v198
	v_and_b32_e32 v231, 0xffff0000, v198
	v_lshlrev_b32_e32 v198, 16, v199
	v_and_b32_e32 v199, 0xffff0000, v199
	v_lshlrev_b32_e32 v232, 16, v200
	v_and_b32_e32 v233, 0xffff0000, v200
	v_lshlrev_b32_e32 v200, 16, v201
	v_and_b32_e32 v201, 0xffff0000, v201
	v_cndmask_b32_e64 v58, v71, v105, s[4:5]
	v_cndmask_b32_e32 v104, v104, v106, vcc
	ds_bpermute_b32 v107, v65, v57
	ds_bpermute_b32 v106, v65, v56
	v_lshlrev_b32_e32 v228, 16, v196
	v_and_b32_e32 v229, 0xffff0000, v196
	v_lshlrev_b32_e32 v196, 16, v197
	v_and_b32_e32 v197, 0xffff0000, v197
	v_lshlrev_b32_e32 v234, 16, v202
	v_and_b32_e32 v235, 0xffff0000, v202
	v_lshlrev_b32_e32 v202, 16, v203
	v_and_b32_e32 v203, 0xffff0000, v203
	v_lshlrev_b32_e32 v236, 16, v204
	v_and_b32_e32 v237, 0xffff0000, v204
	v_lshlrev_b32_e32 v204, 16, v205
	v_and_b32_e32 v205, 0xffff0000, v205
	v_pk_mul_f32 v[108:109], v[58:59], v[222:223] op_sel_hi:[0,1]
	v_pk_mul_f32 v[110:111], v[58:59], v[190:191] op_sel_hi:[0,1]
	v_pk_mul_f32 v[112:113], v[58:59], v[224:225] op_sel_hi:[0,1]
	v_pk_mul_f32 v[114:115], v[58:59], v[192:193] op_sel_hi:[0,1]
	v_pk_mul_f32 v[116:117], v[58:59], v[226:227] op_sel_hi:[0,1]
	v_pk_mul_f32 v[118:119], v[58:59], v[194:195] op_sel_hi:[0,1]
	v_pk_mul_f32 v[122:123], v[104:105], v[230:231] op_sel_hi:[0,1]
	v_pk_mul_f32 v[124:125], v[104:105], v[198:199] op_sel_hi:[0,1]
	v_pk_mul_f32 v[126:127], v[104:105], v[232:233] op_sel_hi:[0,1]
	v_pk_mul_f32 v[130:131], v[104:105], v[200:201] op_sel_hi:[0,1]
	v_pk_mul_f32 v[120:121], v[58:59], v[228:229] op_sel_hi:[0,1]
	v_pk_mul_f32 v[58:59], v[58:59], v[196:197] op_sel_hi:[0,1]
	v_pk_mul_f32 v[132:133], v[104:105], v[234:235] op_sel_hi:[0,1]
	v_pk_mul_f32 v[134:135], v[104:105], v[202:203] op_sel_hi:[0,1]
	v_pk_mul_f32 v[136:137], v[104:105], v[236:237] op_sel_hi:[0,1]
	v_pk_mul_f32 v[104:105], v[104:105], v[204:205] op_sel_hi:[0,1]
	v_pk_fma_f32 v[30:31], v[2:3], v[110:111], v[30:31]
	v_pk_fma_f32 v[28:29], v[0:1], v[108:109], v[28:29]
	v_pk_fma_f32 v[26:27], v[6:7], v[114:115], v[26:27]
	v_pk_fma_f32 v[24:25], v[4:5], v[112:113], v[24:25]
	v_pk_fma_f32 v[22:23], v[10:11], v[118:119], v[22:23]
	v_pk_fma_f32 v[20:21], v[8:9], v[116:117], v[20:21]
	s_waitcnt vmcnt(11)
	v_pk_fma_f32 v[46:47], v[2:3], v[124:125], v[46:47]
	v_pk_fma_f32 v[44:45], v[0:1], v[122:123], v[44:45]
	s_waitcnt vmcnt(10)
	v_pk_fma_f32 v[42:43], v[6:7], v[130:131], v[42:43]
	v_pk_fma_f32 v[40:41], v[4:5], v[126:127], v[40:41]
	v_pk_fma_f32 v[18:19], v[14:15], v[58:59], v[18:19]
	v_pk_fma_f32 v[16:17], v[12:13], v[120:121], v[16:17]
	s_waitcnt vmcnt(8)
	v_pk_fma_f32 v[34:35], v[14:15], v[104:105], v[34:35]
	v_pk_mul_f32 v[58:59], v[30:31], v[30:31]
	v_pk_mul_f32 v[104:105], v[28:29], v[28:29]
	global_store_dwordx4 v[60:61], v[28:31], off offset:-3072 nt
	v_pk_mul_f32 v[108:109], v[26:27], v[26:27]
	v_pk_mul_f32 v[110:111], v[24:25], v[24:25]
	global_store_dwordx4 v[60:61], v[24:27], off offset:-2048 nt
	global_store_dwordx4 v[60:61], v[20:23], off offset:-1024 nt
	v_mul_f32_e32 v60, v21, v21
	v_mul_f32_e32 v112, v23, v23
	v_pk_mul_f32 v[114:115], v[46:47], v[46:47]
	v_pk_mul_f32 v[116:117], v[44:45], v[44:45]
	v_pk_mul_f32 v[118:119], v[42:43], v[42:43]
	v_pk_mul_f32 v[120:121], v[40:41], v[40:41]
	v_pk_fma_f32 v[38:39], v[10:11], v[134:135], v[38:39]
	v_pk_fma_f32 v[36:37], v[8:9], v[132:133], v[36:37]
	v_mul_f32_e32 v71, v16, v16
	v_mul_f32_e32 v125, v17, v17
	v_pk_mov_b32 v[126:127], v[104:105], v[58:59] op_sel:[1,0]
	v_mov_b32_e32 v105, v59
	v_pk_mov_b32 v[58:59], v[110:111], v[108:109] op_sel:[1,0]
	v_mov_b32_e32 v111, v109
	v_pk_fma_f32 v[60:61], v[20:21], v[20:21], v[60:61] op_sel_hi:[1,1,0]
	v_pk_fma_f32 v[108:109], v[22:23], v[22:23], v[112:113] op_sel_hi:[1,1,0]
	v_pk_mov_b32 v[112:113], v[116:117], v[114:115] op_sel:[1,0]
	v_mov_b32_e32 v117, v115
	v_pk_mov_b32 v[114:115], v[120:121], v[118:119] op_sel:[1,0]
	v_mov_b32_e32 v121, v119
	v_pk_fma_f32 v[32:33], v[12:13], v[136:137], v[32:33]
	v_mul_f32_e32 v122, v37, v37
	v_mul_f32_e32 v124, v39, v39
	v_pk_add_f32 v[104:105], v[126:127], v[104:105]
	v_pk_add_f32 v[58:59], v[58:59], v[110:111]
	v_mov_b32_e32 v61, v71
	v_mov_b32_e32 v109, v125
	v_pk_add_f32 v[110:111], v[112:113], v[116:117]
	v_pk_add_f32 v[112:113], v[114:115], v[120:121]
	s_waitcnt lgkmcnt(0)
	v_pk_add_f32 v[56:57], v[56:57], v[106:107]
	v_mul_f32_e32 v130, v18, v18
	v_mul_f32_e32 v131, v19, v19
	v_mul_f32_e32 v132, v32, v32
	v_mul_f32_e32 v133, v33, v33
	v_mul_f32_e32 v134, v34, v34
	v_mul_f32_e32 v135, v35, v35
	v_pk_fma_f32 v[118:119], v[36:37], v[36:37], v[122:123] op_sel_hi:[1,1,0]
	v_pk_fma_f32 v[122:123], v[38:39], v[38:39], v[124:125] op_sel_hi:[1,1,0]
	v_pk_add_f32 v[60:61], v[60:61], v[108:109]
	v_pk_add_f32 v[104:105], v[104:105], v[104:105] op_sel:[0,1] op_sel_hi:[1,0]
	v_pk_add_f32 v[58:59], v[58:59], v[58:59] op_sel:[0,1] op_sel_hi:[1,0]
	v_pk_add_f32 v[108:109], v[110:111], v[110:111] op_sel:[0,1] op_sel_hi:[1,0]
	v_pk_add_f32 v[110:111], v[112:113], v[112:113] op_sel:[0,1] op_sel_hi:[1,0]
	ds_bpermute_b32 v113, v66, v57
	ds_bpermute_b32 v112, v66, v56
	v_mov_b32_e32 v119, v132
	v_mov_b32_e32 v123, v133
	v_mov_b32_e32 v105, v130
	v_mov_b32_e32 v59, v131
	v_mov_b32_e32 v109, v134
	v_mov_b32_e32 v111, v135
	v_pk_add_f32 v[106:107], v[118:119], v[122:123]
	v_pk_add_f32 v[58:59], v[104:105], v[58:59]
	v_pk_add_f32 v[104:105], v[108:109], v[110:111]
	v_pk_add_f32 v[58:59], v[60:61], v[58:59]
	v_pk_add_f32 v[60:61], v[106:107], v[104:105]
	v_mov_b32_e32 v105, v58
	v_mov_b32_e32 v104, v60
	v_mov_b32_e32 v58, v61
	s_waitcnt lgkmcnt(0)
	v_pk_add_f32 v[56:57], v[56:57], v[112:113]
	v_pk_add_f32 v[58:59], v[104:105], v[58:59]
	ds_bpermute_b32 v61, v67, v57
	ds_bpermute_b32 v60, v67, v56
	ds_bpermute_b32 v105, v64, v59
	ds_bpermute_b32 v104, v64, v58
	global_store_dwordx4 v[48:49], v[16:19], off offset:-4096 nt
	global_store_dwordx4 v[48:49], v[44:47], off offset:-3072 nt
	s_waitcnt lgkmcnt(2)
	v_pk_add_f32 v[56:57], v[56:57], v[60:61]
	ds_bpermute_b32 v61, v68, v57
	s_waitcnt lgkmcnt(1)
	v_pk_add_f32 v[58:59], v[58:59], v[104:105]
	ds_bpermute_b32 v60, v68, v56
	ds_bpermute_b32 v105, v65, v59
	ds_bpermute_b32 v104, v65, v58
	global_store_dwordx4 v[48:49], v[40:43], off offset:-2048 nt
	global_store_dwordx4 v[48:49], v[36:39], off offset:-1024 nt
	global_store_dwordx4 v[48:49], v[32:35], off nt
	s_waitcnt lgkmcnt(2)
	v_pk_add_f32 v[56:57], v[56:57], v[60:61]
	ds_bpermute_b32 v61, v69, v57
	s_waitcnt lgkmcnt(1)
	v_pk_add_f32 v[58:59], v[58:59], v[104:105]
	ds_bpermute_b32 v60, v69, v56
	ds_bpermute_b32 v105, v66, v59
	ds_bpermute_b32 v104, v66, v58
	v_lshl_add_u64 v[48:49], v[48:49], 0, s[12:13]
	s_waitcnt lgkmcnt(2)
	v_pk_add_f32 v[56:57], v[56:57], v[60:61]
	s_nop 0
	v_pk_fma_f32 v[56:57], v[56:57], s[20:21], v[52:53] op_sel_hi:[1,0,0]
	s_waitcnt lgkmcnt(0)
	v_pk_add_f32 v[58:59], v[58:59], v[104:105]
	ds_bpermute_b32 v61, v67, v59
	ds_bpermute_b32 v60, v67, v58
	v_mul_f32_e32 v71, 0x4b800000, v57
	v_cmp_gt_f32_e64 s[4:5], s2, v57
	v_mul_f32_e32 v104, 0x4b800000, v56
	v_cmp_gt_f32_e32 vcc, s2, v56
	v_cndmask_b32_e64 v57, v57, v71, s[4:5]
	v_rsq_f32_e32 v71, v57
	v_cndmask_b32_e32 v56, v56, v104, vcc
	v_rsq_f32_e32 v104, v56
	s_waitcnt lgkmcnt(0)
	v_pk_add_f32 v[56:57], v[58:59], v[60:61]
	ds_bpermute_b32 v59, v68, v57
	ds_bpermute_b32 v58, v68, v56
	v_mul_f32_e32 v60, 0x45800000, v71
	v_mul_f32_e32 v61, 0x45800000, v104
	v_cndmask_b32_e64 v60, v71, v60, s[4:5]
	v_cndmask_b32_e32 v104, v104, v61, vcc
	v_pk_mul_f32 v[72:73], v[72:73], v[60:61] op_sel_hi:[1,0]
	v_pk_mul_f32 v[74:75], v[74:75], v[60:61] op_sel_hi:[1,0]
	v_pk_mul_f32 v[76:77], v[76:77], v[60:61] op_sel_hi:[1,0]
	v_pk_mul_f32 v[78:79], v[78:79], v[60:61] op_sel_hi:[1,0]
	v_pk_mul_f32 v[80:81], v[80:81], v[60:61] op_sel_hi:[1,0]
	v_pk_mul_f32 v[82:83], v[82:83], v[60:61] op_sel_hi:[1,0]
	v_pk_mul_f32 v[84:85], v[84:85], v[60:61] op_sel_hi:[1,0]
	v_pk_mul_f32 v[60:61], v[86:87], v[60:61] op_sel_hi:[1,0]
	v_pk_mul_f32 v[86:87], v[88:89], v[104:105] op_sel_hi:[1,0]
	v_pk_mul_f32 v[88:89], v[90:91], v[104:105] op_sel_hi:[1,0]
	v_pk_mul_f32 v[90:91], v[92:93], v[104:105] op_sel_hi:[1,0]
	v_pk_mul_f32 v[92:93], v[94:95], v[104:105] op_sel_hi:[1,0]
	v_pk_mul_f32 v[94:95], v[96:97], v[104:105] op_sel_hi:[1,0]
	v_pk_mul_f32 v[96:97], v[98:99], v[104:105] op_sel_hi:[1,0]
	v_pk_mul_f32 v[98:99], v[100:101], v[104:105] op_sel_hi:[1,0]
	v_pk_mul_f32 v[100:101], v[102:103], v[104:105] op_sel_hi:[1,0]
	v_cvt_pk_bf16_f32 v72, v72, v73
	v_cvt_pk_bf16_f32 v73, v74, v75
	v_cvt_pk_bf16_f32 v74, v76, v77
	v_cvt_pk_bf16_f32 v75, v78, v79
	v_cvt_pk_bf16_f32 v76, v80, v81
	v_cvt_pk_bf16_f32 v77, v82, v83
	v_cvt_pk_bf16_f32 v78, v84, v85
	v_cvt_pk_bf16_f32 v79, v60, v61
	v_cvt_pk_bf16_f32 v60, v86, v87
	v_cvt_pk_bf16_f32 v61, v88, v89
	v_cvt_pk_bf16_f32 v80, v90, v91
	v_cvt_pk_bf16_f32 v81, v92, v93
	v_cvt_pk_bf16_f32 v82, v94, v95
	v_cvt_pk_bf16_f32 v83, v96, v97
	v_cvt_pk_bf16_f32 v84, v98, v99
	v_cvt_pk_bf16_f32 v85, v100, v101
	global_store_dwordx2 v[54:55], v[72:73], off
	global_store_dwordx2 v[54:55], v[74:75], off offset:512
	global_store_dwordx2 v[54:55], v[76:77], off offset:1024
	global_store_dwordx2 v[54:55], v[78:79], off offset:1536
	global_store_dwordx2 v[54:55], v[60:61], off offset:2048
	global_store_dwordx2 v[54:55], v[80:81], off offset:2560
	global_store_dwordx2 v[54:55], v[82:83], off offset:3072
	global_store_dwordx2 v[54:55], v[84:85], off offset:3584
	s_waitcnt lgkmcnt(0)
	v_pk_add_f32 v[54:55], v[56:57], v[58:59]
	ds_bpermute_b32 v57, v69, v55
	ds_bpermute_b32 v56, v69, v54
	s_waitcnt lgkmcnt(0)
	v_pk_add_f32 v[54:55], v[54:55], v[56:57]
	s_nop 0
	v_pk_fma_f32 v[54:55], v[54:55], s[20:21], v[52:53] op_sel_hi:[1,0,0]
	s_nop 0
	v_mul_f32_e32 v56, 0x4b800000, v55
	v_cmp_gt_f32_e64 s[4:5], s2, v55
	v_mul_f32_e32 v57, 0x4b800000, v54
	v_cmp_gt_f32_e32 vcc, s2, v54
	v_cndmask_b32_e64 v55, v55, v56, s[4:5]
	v_rsq_f32_e32 v55, v55
	v_cndmask_b32_e32 v54, v54, v57, vcc
	v_rsq_f32_e32 v56, v54
	v_mul_f32_e32 v54, 0x45800000, v55
	v_cndmask_b32_e64 v54, v55, v54, s[4:5]
	v_mul_f32_e32 v57, 0x45800000, v56
	v_cndmask_b32_e32 v56, v56, v57, vcc
	v_pk_mul_f32 v[28:29], v[28:29], v[54:55] op_sel_hi:[1,0]
	v_pk_mul_f32 v[30:31], v[30:31], v[54:55] op_sel_hi:[1,0]
	v_pk_mul_f32 v[24:25], v[24:25], v[54:55] op_sel_hi:[1,0]
	v_pk_mul_f32 v[26:27], v[26:27], v[54:55] op_sel_hi:[1,0]
	v_pk_mul_f32 v[20:21], v[20:21], v[54:55] op_sel_hi:[1,0]
	v_pk_mul_f32 v[22:23], v[22:23], v[54:55] op_sel_hi:[1,0]
	v_pk_mul_f32 v[16:17], v[16:17], v[54:55] op_sel_hi:[1,0]
	v_pk_mul_f32 v[18:19], v[18:19], v[54:55] op_sel_hi:[1,0]
	v_pk_mul_f32 v[44:45], v[44:45], v[56:57] op_sel_hi:[1,0]
	v_pk_mul_f32 v[46:47], v[46:47], v[56:57] op_sel_hi:[1,0]
	v_pk_mul_f32 v[40:41], v[40:41], v[56:57] op_sel_hi:[1,0]
	v_pk_mul_f32 v[42:43], v[42:43], v[56:57] op_sel_hi:[1,0]
	v_pk_mul_f32 v[36:37], v[36:37], v[56:57] op_sel_hi:[1,0]
	v_pk_mul_f32 v[38:39], v[38:39], v[56:57] op_sel_hi:[1,0]
	v_pk_mul_f32 v[32:33], v[32:33], v[56:57] op_sel_hi:[1,0]
	v_pk_mul_f32 v[34:35], v[34:35], v[56:57] op_sel_hi:[1,0]
	v_cvt_pk_bf16_f32 v28, v28, v29
	v_cvt_pk_bf16_f32 v29, v30, v31
	v_cvt_pk_bf16_f32 v24, v24, v25
	v_cvt_pk_bf16_f32 v25, v26, v27
	v_cvt_pk_bf16_f32 v20, v20, v21
	v_cvt_pk_bf16_f32 v21, v22, v23
	v_cvt_pk_bf16_f32 v16, v16, v17
	v_cvt_pk_bf16_f32 v17, v18, v19
	v_cvt_pk_bf16_f32 v18, v44, v45
	v_cvt_pk_bf16_f32 v19, v46, v47
	v_cvt_pk_bf16_f32 v22, v40, v41
	v_cvt_pk_bf16_f32 v23, v42, v43
	v_cvt_pk_bf16_f32 v26, v36, v37
	v_cvt_pk_bf16_f32 v27, v38, v39
	v_cvt_pk_bf16_f32 v30, v32, v33
	v_cvt_pk_bf16_f32 v31, v34, v35
	global_store_dwordx2 v[62:63], v[28:29], off
	global_store_dwordx2 v[62:63], v[24:25], off offset:512
	global_store_dwordx2 v[62:63], v[20:21], off offset:1024
	global_store_dwordx2 v[62:63], v[16:17], off offset:1536
	global_store_dwordx2 v[62:63], v[18:19], off offset:2048
	global_store_dwordx2 v[62:63], v[22:23], off offset:2560
	global_store_dwordx2 v[62:63], v[26:27], off offset:3072
	global_store_dwordx2 v[62:63], v[30:31], off offset:3584
	s_cbranch_scc1 .LBB0_795
